# v49 + gate/up epilogue: 24 register copies of prefetched bias/rowss dropped (consumers read prefetch registers)
# baseline (speedup 1.0000x reference)
; __device__ __forceinline__ unsigned pk_bf16(float lo, float hi) { f32x2 v = {lo, hi}; bf16x2_t b = __builtin_convertvector(v, bf16x2_t); return __builtin_bit_cast(unsigned, b); }
;     __device__ __forceinline__ void operator()(const f32x4 (&acc)[2][2][4][2], const Unit& u, int wr, int wc, int fr, int fq) const {
;     ...
; #pragma unroll
;         for (int ai = 0; ai < 2; ++ai)
; #pragma unroll
;             for (int m = 0; m < 4; ++m) {
;                 float o[8]; const float rv = rsqrtf(rowss[row0 + ai * HALF + m * 16] * (1.0f / 1024.0f) + 1e-6f);
; #pragma unroll
;                 for (int n = 0; n < 2; ++n)
; #pragma unroll
;                     for (int j = 0; j < 4; ++j) { const float g = acc[ai][0][m][n][j] * rv + bz[0][n][j], up = acc[ai][1][m][n][j] * rv + bz[1][n][j];
;                         o[4 * n + j] = g * __builtin_amdgcn_rcpf(1.0f + __expf(-g)) * up; }
;                 u32x4 w; w.x = pk_bf16(o[0], o[1]); w.y = pk_bf16(o[2], o[3]); w.z = pk_bf16(o[4], o[5]); w.w = pk_bf16(o[6], o[7]);
;                 *(u32x4*)(act + (size_t)(row0 + ai * HALF + m * 16) * 2816 + col0) = w;
;             }
.LBB0_907:
	s_ashr_i32 s4, s34, 6
	s_mul_hi_i32 s5, s4, 0x5800
	s_mulk_i32 s4, 0x5800
	v_lshl_add_u32 v156, s34, 8, v162
	s_add_u32 s34, s14, s4
	s_addc_u32 s37, s15, s5
	s_lshl_b32 s4, s31, 8
	s_ashr_i32 s5, s4, 31
	s_lshl_b64 s[4:5], s[4:5], 2
	s_add_u32 s4, s34, s4
	s_addc_u32 s5, s37, s5
	s_add_u32 s4, s4, s30
	v_ashrrev_i32_e32 v157, 31, v156
	s_addc_u32 s5, s5, 0
	v_lshl_add_u64 v[158:159], v[156:157], 2, s[42:43]
	v_lshl_or_b32 v160, s31, 7, v164
	v_ashrrev_i32_e32 v161, 31, v160
	s_movk_i32 s12, 0x1600
	s_mov_b64 s[54:55], -1
	s_waitcnt vmcnt(8)
	v_fmamk_f32 v157, v147, 0x3a800000, v227
	s_nop 0
	v_rsq_f32_e32 v157, v157
	s_nop 0
	v_mov_b32_e32 v168, v157
	v_pk_fma_f32 v[142:143], v[142:143], v[168:169], v[246:247] op_sel_hi:[1,0,1]
	v_pk_fma_f32 v[134:135], v[134:135], v[168:169], v[238:239] op_sel_hi:[1,0,1]
	v_mul_f32_e32 v157, 0xbfb8aa3b, v142
	v_exp_f32_e32 v157, v157
	v_pk_fma_f32 v[136:137], v[136:137], v[168:169], v[240:241] op_sel_hi:[1,0,1]
	v_pk_fma_f32 v[138:139], v[138:139], v[168:169], v[242:243] op_sel_hi:[1,0,1]
	v_pk_fma_f32 v[130:131], v[130:131], v[168:169], v[174:175] op_sel_hi:[1,0,1]
	v_add_f32_e32 v157, 1.0, v157
	v_rcp_f32_e32 v170, v157
	v_mul_f32_e32 v157, 0xbfb8aa3b, v143
	v_exp_f32_e32 v157, v157
	v_pk_fma_f32 v[132:133], v[132:133], v[168:169], v[176:177] op_sel_hi:[1,0,1]
	v_add_f32_e32 v157, 1.0, v157
	v_rcp_f32_e32 v171, v157
	s_nop 0
	v_pk_mul_f32 v[142:143], v[142:143], v[170:171]
	s_nop 0
	v_pk_mul_f32 v[134:135], v[134:135], v[142:143]
	v_pk_fma_f32 v[142:143], v[144:145], v[168:169], v[248:249] op_sel_hi:[1,0,1]
	s_nop 0
	v_mul_f32_e32 v144, 0xbfb8aa3b, v142
	v_mul_f32_e32 v145, 0xbfb8aa3b, v143
	v_exp_f32_e32 v144, v144
	v_exp_f32_e32 v145, v145
	v_add_f32_e32 v144, 1.0, v144
	v_add_f32_e32 v145, 1.0, v145
	v_rcp_f32_e32 v144, v144
	v_rcp_f32_e32 v145, v145
	s_nop 0
	v_pk_mul_f32 v[142:143], v[142:143], v[144:145]
	s_nop 0
	v_pk_mul_f32 v[136:137], v[136:137], v[142:143]
	v_mul_f32_e32 v142, 0xbfb8aa3b, v138
	v_mul_f32_e32 v143, 0xbfb8aa3b, v139
	v_exp_f32_e32 v142, v142
	v_exp_f32_e32 v143, v143
	v_add_f32_e32 v142, 1.0, v142
	v_add_f32_e32 v143, 1.0, v143
	v_rcp_f32_e32 v142, v142
	v_rcp_f32_e32 v143, v143
	s_nop 0
	v_pk_mul_f32 v[138:139], v[138:139], v[142:143]
	s_nop 0
	v_pk_mul_f32 v[138:139], v[130:131], v[138:139]
	v_pk_fma_f32 v[130:131], v[140:141], v[168:169], v[244:245] op_sel_hi:[1,0,1]
	s_nop 0
	v_mul_f32_e32 v140, 0xbfb8aa3b, v130
	v_mul_f32_e32 v141, 0xbfb8aa3b, v131
	v_exp_f32_e32 v140, v140
	v_exp_f32_e32 v141, v141
	v_add_f32_e32 v140, 1.0, v140
	v_add_f32_e32 v141, 1.0, v141
	v_rcp_f32_e32 v140, v140
	v_rcp_f32_e32 v141, v141
	s_nop 0
	v_pk_mul_f32 v[130:131], v[130:131], v[140:141]
	s_nop 0
	v_pk_mul_f32 v[140:141], v[132:133], v[130:131]
	v_cvt_pk_bf16_f32 v130, v134, v135
	v_mov_b64_e32 v[134:135], s[2:3]
	v_cvt_pk_bf16_f32 v131, v136, v137
	v_cvt_pk_bf16_f32 v132, v138, v139
	v_mad_i64_i32 v[138:139], s[4:5], v156, s12, v[134:135]
	v_lshlrev_b64 v[136:137], 1, v[160:161]
	v_cvt_pk_bf16_f32 v133, v140, v141
	v_lshl_add_u64 v[138:139], v[138:139], 0, v[136:137]
	global_store_dwordx4 v[138:139], v[130:133], off
	s_nop 1
	v_or_b32_e32 v130, 16, v156
	v_fmamk_f32 v131, v149, 0x3a800000, v227
	s_nop 0
	v_rsq_f32_e32 v131, v131
	s_nop 0
	v_mov_b32_e32 v132, v131
	v_pk_fma_f32 v[124:125], v[124:125], v[132:133], v[246:247] op_sel_hi:[1,0,1]
	v_pk_fma_f32 v[116:117], v[116:117], v[132:133], v[238:239] op_sel_hi:[1,0,1]
	v_mul_f32_e32 v131, 0xbfb8aa3b, v124
	v_exp_f32_e32 v131, v131
	v_pk_fma_f32 v[118:119], v[118:119], v[132:133], v[240:241] op_sel_hi:[1,0,1]
	v_pk_fma_f32 v[120:121], v[120:121], v[132:133], v[242:243] op_sel_hi:[1,0,1]
	v_pk_fma_f32 v[112:113], v[112:113], v[132:133], v[174:175] op_sel_hi:[1,0,1]
	v_add_f32_e32 v131, 1.0, v131
	v_rcp_f32_e32 v138, v131
	v_mul_f32_e32 v131, 0xbfb8aa3b, v125
	v_exp_f32_e32 v131, v131
	v_pk_fma_f32 v[114:115], v[114:115], v[132:133], v[176:177] op_sel_hi:[1,0,1]
	v_add_f32_e32 v131, 1.0, v131
	v_rcp_f32_e32 v139, v131
	s_nop 0
	v_pk_mul_f32 v[124:125], v[124:125], v[138:139]
	s_nop 0
	v_pk_mul_f32 v[116:117], v[116:117], v[124:125]
	v_pk_fma_f32 v[124:125], v[126:127], v[132:133], v[248:249] op_sel_hi:[1,0,1]
	s_nop 0
	v_mul_f32_e32 v126, 0xbfb8aa3b, v124
	v_mul_f32_e32 v127, 0xbfb8aa3b, v125
	v_exp_f32_e32 v126, v126
	v_exp_f32_e32 v127, v127
	v_add_f32_e32 v126, 1.0, v126
	v_add_f32_e32 v127, 1.0, v127
	v_rcp_f32_e32 v126, v126
	v_rcp_f32_e32 v127, v127
	s_nop 0
	v_pk_mul_f32 v[124:125], v[124:125], v[126:127]
	s_nop 0
	v_pk_mul_f32 v[118:119], v[118:119], v[124:125]
	v_mul_f32_e32 v124, 0xbfb8aa3b, v120
	v_mul_f32_e32 v125, 0xbfb8aa3b, v121
	v_exp_f32_e32 v124, v124
	v_exp_f32_e32 v125, v125
	v_add_f32_e32 v124, 1.0, v124
	v_add_f32_e32 v125, 1.0, v125
	v_rcp_f32_e32 v124, v124
	v_rcp_f32_e32 v125, v125
	s_nop 0
	v_pk_mul_f32 v[120:121], v[120:121], v[124:125]
	s_nop 0
	v_pk_mul_f32 v[120:121], v[112:113], v[120:121]
	v_pk_fma_f32 v[112:113], v[122:123], v[132:133], v[244:245] op_sel_hi:[1,0,1]
	s_nop 0
	v_mul_f32_e32 v122, 0xbfb8aa3b, v112
	v_mul_f32_e32 v123, 0xbfb8aa3b, v113
	v_exp_f32_e32 v122, v122
	v_exp_f32_e32 v123, v123
	v_add_f32_e32 v122, 1.0, v122
	v_add_f32_e32 v123, 1.0, v123
	v_rcp_f32_e32 v122, v122
	v_rcp_f32_e32 v123, v123
	s_nop 0
	v_pk_mul_f32 v[112:113], v[112:113], v[122:123]
	s_nop 0
	v_pk_mul_f32 v[122:123], v[114:115], v[112:113]
	v_cvt_pk_bf16_f32 v112, v116, v117
	v_mad_i64_i32 v[116:117], s[4:5], v130, s12, v[134:135]
	v_cvt_pk_bf16_f32 v113, v118, v119
	v_cvt_pk_bf16_f32 v114, v120, v121
	v_cvt_pk_bf16_f32 v115, v122, v123
	v_lshl_add_u64 v[116:117], v[116:117], 0, v[136:137]
; __device__ __forceinline__ unsigned pk_bf16(float lo, float hi) { f32x2 v = {lo, hi}; bf16x2_t b = __builtin_convertvector(v, bf16x2_t); return __builtin_bit_cast(unsigned, b); }
;     __device__ __forceinline__ void operator()(const f32x4 (&acc)[2][2][4][2], const Unit& u, int wr, int wc, int fr, int fq) const {
;     ...
; #pragma unroll
;         for (int ai = 0; ai < 2; ++ai)
; #pragma unroll
;             for (int m = 0; m < 4; ++m) {
;                 float o[8]; const float rv = rsqrtf(rowss[row0 + ai * HALF + m * 16] * (1.0f / 1024.0f) + 1e-6f);
; #pragma unroll
;                 for (int n = 0; n < 2; ++n)
; #pragma unroll
;                     for (int j = 0; j < 4; ++j) { const float g = acc[ai][0][m][n][j] * rv + bz[0][n][j], up = acc[ai][1][m][n][j] * rv + bz[1][n][j];
;                         o[4 * n + j] = g * __builtin_amdgcn_rcpf(1.0f + __expf(-g)) * up; }
;                 u32x4 w; w.x = pk_bf16(o[0], o[1]); w.y = pk_bf16(o[2], o[3]); w.z = pk_bf16(o[4], o[5]); w.w = pk_bf16(o[6], o[7]);
;                 *(u32x4*)(act + (size_t)(row0 + ai * HALF + m * 16) * 2816 + col0) = w;
;             }
	global_store_dwordx4 v[116:117], v[112:115], off
	s_nop 1
	v_or_b32_e32 v112, 32, v156
	v_fmamk_f32 v113, v151, 0x3a800000, v227
	s_nop 0
	v_rsq_f32_e32 v113, v113
	s_nop 0
	v_mov_b32_e32 v114, v113
	v_pk_fma_f32 v[108:109], v[108:109], v[114:115], v[246:247] op_sel_hi:[1,0,1]
	v_pk_fma_f32 v[100:101], v[100:101], v[114:115], v[238:239] op_sel_hi:[1,0,1]
	v_mul_f32_e32 v113, 0xbfb8aa3b, v108
	v_exp_f32_e32 v113, v113
	v_pk_fma_f32 v[102:103], v[102:103], v[114:115], v[240:241] op_sel_hi:[1,0,1]
	v_pk_fma_f32 v[104:105], v[104:105], v[114:115], v[242:243] op_sel_hi:[1,0,1]
	v_pk_fma_f32 v[96:97], v[96:97], v[114:115], v[174:175] op_sel_hi:[1,0,1]
	v_add_f32_e32 v113, 1.0, v113
	v_rcp_f32_e32 v116, v113
	v_mul_f32_e32 v113, 0xbfb8aa3b, v109
	v_exp_f32_e32 v113, v113
	v_pk_fma_f32 v[98:99], v[98:99], v[114:115], v[176:177] op_sel_hi:[1,0,1]
	v_add_f32_e32 v113, 1.0, v113
	v_rcp_f32_e32 v117, v113
	s_nop 0
	v_pk_mul_f32 v[108:109], v[108:109], v[116:117]
	s_nop 0
	v_pk_mul_f32 v[100:101], v[100:101], v[108:109]
	v_pk_fma_f32 v[108:109], v[110:111], v[114:115], v[248:249] op_sel_hi:[1,0,1]
	s_nop 0
	v_mul_f32_e32 v110, 0xbfb8aa3b, v108
	v_mul_f32_e32 v111, 0xbfb8aa3b, v109
	v_exp_f32_e32 v110, v110
	v_exp_f32_e32 v111, v111
	v_add_f32_e32 v110, 1.0, v110
	v_add_f32_e32 v111, 1.0, v111
	v_rcp_f32_e32 v110, v110
	v_rcp_f32_e32 v111, v111
	s_nop 0
	v_pk_mul_f32 v[108:109], v[108:109], v[110:111]
	s_nop 0
	v_pk_mul_f32 v[102:103], v[102:103], v[108:109]
	v_mul_f32_e32 v108, 0xbfb8aa3b, v104
	v_mul_f32_e32 v109, 0xbfb8aa3b, v105
	v_exp_f32_e32 v108, v108
	v_exp_f32_e32 v109, v109
	v_add_f32_e32 v108, 1.0, v108
	v_add_f32_e32 v109, 1.0, v109
	v_rcp_f32_e32 v108, v108
	v_rcp_f32_e32 v109, v109
	s_nop 0
	v_pk_mul_f32 v[104:105], v[104:105], v[108:109]
	s_nop 0
	v_pk_mul_f32 v[104:105], v[96:97], v[104:105]
	v_pk_fma_f32 v[96:97], v[106:107], v[114:115], v[244:245] op_sel_hi:[1,0,1]
	s_nop 0
	v_mul_f32_e32 v106, 0xbfb8aa3b, v96
	v_mul_f32_e32 v107, 0xbfb8aa3b, v97
	v_exp_f32_e32 v106, v106
	v_exp_f32_e32 v107, v107
	v_add_f32_e32 v106, 1.0, v106
	v_add_f32_e32 v107, 1.0, v107
	v_rcp_f32_e32 v106, v106
	v_rcp_f32_e32 v107, v107
	s_nop 0
	v_pk_mul_f32 v[96:97], v[96:97], v[106:107]
	s_nop 0
	v_pk_mul_f32 v[106:107], v[98:99], v[96:97]
	v_cvt_pk_bf16_f32 v96, v100, v101
	v_mad_i64_i32 v[100:101], s[4:5], v112, s12, v[134:135]
	v_cvt_pk_bf16_f32 v97, v102, v103
	v_cvt_pk_bf16_f32 v98, v104, v105
	v_cvt_pk_bf16_f32 v99, v106, v107
	v_lshl_add_u64 v[100:101], v[100:101], 0, v[136:137]
	global_store_dwordx4 v[100:101], v[96:99], off
	s_nop 1
	v_or_b32_e32 v96, 48, v156
	v_fmamk_f32 v97, v153, 0x3a800000, v227
	s_nop 0
	v_rsq_f32_e32 v97, v97
	s_nop 0
	v_mov_b32_e32 v98, v97
	v_pk_fma_f32 v[92:93], v[92:93], v[98:99], v[246:247] op_sel_hi:[1,0,1]
	v_pk_fma_f32 v[84:85], v[84:85], v[98:99], v[238:239] op_sel_hi:[1,0,1]
	v_mul_f32_e32 v97, 0xbfb8aa3b, v92
	v_exp_f32_e32 v97, v97
	v_pk_fma_f32 v[86:87], v[86:87], v[98:99], v[240:241] op_sel_hi:[1,0,1]
	v_pk_fma_f32 v[88:89], v[88:89], v[98:99], v[242:243] op_sel_hi:[1,0,1]
	v_pk_fma_f32 v[80:81], v[80:81], v[98:99], v[174:175] op_sel_hi:[1,0,1]
	v_add_f32_e32 v97, 1.0, v97
	v_rcp_f32_e32 v100, v97
	v_mul_f32_e32 v97, 0xbfb8aa3b, v93
	v_exp_f32_e32 v97, v97
	v_pk_fma_f32 v[82:83], v[82:83], v[98:99], v[176:177] op_sel_hi:[1,0,1]
	v_add_f32_e32 v97, 1.0, v97
	v_rcp_f32_e32 v101, v97
	s_nop 0
	v_pk_mul_f32 v[92:93], v[92:93], v[100:101]
	s_nop 0
	v_pk_mul_f32 v[84:85], v[84:85], v[92:93]
	v_pk_fma_f32 v[92:93], v[94:95], v[98:99], v[248:249] op_sel_hi:[1,0,1]
	s_nop 0
	v_mul_f32_e32 v94, 0xbfb8aa3b, v92
	v_mul_f32_e32 v95, 0xbfb8aa3b, v93
	v_exp_f32_e32 v94, v94
	v_exp_f32_e32 v95, v95
	v_add_f32_e32 v94, 1.0, v94
	v_add_f32_e32 v95, 1.0, v95
	v_rcp_f32_e32 v94, v94
	v_rcp_f32_e32 v95, v95
	s_nop 0
	v_pk_mul_f32 v[92:93], v[92:93], v[94:95]
	s_nop 0
	v_pk_mul_f32 v[86:87], v[86:87], v[92:93]
	v_mul_f32_e32 v92, 0xbfb8aa3b, v88
	v_mul_f32_e32 v93, 0xbfb8aa3b, v89
	v_exp_f32_e32 v92, v92
	v_exp_f32_e32 v93, v93
	v_add_f32_e32 v92, 1.0, v92
	v_add_f32_e32 v93, 1.0, v93
	v_rcp_f32_e32 v92, v92
	v_rcp_f32_e32 v93, v93
	s_nop 0
	v_pk_mul_f32 v[88:89], v[88:89], v[92:93]
	s_nop 0
	v_pk_mul_f32 v[88:89], v[80:81], v[88:89]
	v_pk_fma_f32 v[80:81], v[90:91], v[98:99], v[244:245] op_sel_hi:[1,0,1]
	s_nop 0
	v_mul_f32_e32 v90, 0xbfb8aa3b, v80
	v_mul_f32_e32 v91, 0xbfb8aa3b, v81
	v_exp_f32_e32 v90, v90
	v_exp_f32_e32 v91, v91
	v_add_f32_e32 v90, 1.0, v90
	v_add_f32_e32 v91, 1.0, v91
	v_rcp_f32_e32 v90, v90
	v_rcp_f32_e32 v91, v91
	s_nop 0
	v_pk_mul_f32 v[80:81], v[80:81], v[90:91]
	s_nop 0
	v_pk_mul_f32 v[90:91], v[82:83], v[80:81]
	v_cvt_pk_bf16_f32 v80, v84, v85
	v_mad_i64_i32 v[84:85], s[4:5], v96, s12, v[134:135]
	v_cvt_pk_bf16_f32 v81, v86, v87
	v_cvt_pk_bf16_f32 v82, v88, v89
	v_cvt_pk_bf16_f32 v83, v90, v91
	v_lshl_add_u64 v[84:85], v[84:85], 0, v[136:137]
	global_store_dwordx4 v[84:85], v[80:83], off
	s_nop 0
	s_nop 0
	v_add_u32_e32 v81, 0x80, v156
	v_fmamk_f32 v80, v155, 0x3a800000, v227
	s_nop 0
	v_rsq_f32_e32 v80, v80
	s_nop 0
	v_pk_fma_f32 v[76:77], v[76:77], v[80:81], v[246:247] op_sel_hi:[1,0,1]
	v_pk_fma_f32 v[68:69], v[68:69], v[80:81], v[238:239] op_sel_hi:[1,0,1]
	v_mul_f32_e32 v82, 0xbfb8aa3b, v76
	v_mul_f32_e32 v83, 0xbfb8aa3b, v77
	v_exp_f32_e32 v82, v82
	v_exp_f32_e32 v83, v83
	v_pk_fma_f32 v[70:71], v[70:71], v[80:81], v[240:241] op_sel_hi:[1,0,1]
	v_pk_fma_f32 v[72:73], v[72:73], v[80:81], v[242:243] op_sel_hi:[1,0,1]
	v_add_f32_e32 v82, 1.0, v82
	v_add_f32_e32 v83, 1.0, v83
	v_rcp_f32_e32 v82, v82
	v_rcp_f32_e32 v83, v83
	v_pk_fma_f32 v[64:65], v[64:65], v[80:81], v[174:175] op_sel_hi:[1,0,1]
; __device__ __forceinline__ unsigned pk_bf16(float lo, float hi) { f32x2 v = {lo, hi}; bf16x2_t b = __builtin_convertvector(v, bf16x2_t); return __builtin_bit_cast(unsigned, b); }
;     __device__ __forceinline__ void operator()(const f32x4 (&acc)[2][2][4][2], const Unit& u, int wr, int wc, int fr, int fq) const {
;     ...
; #pragma unroll
;         for (int ai = 0; ai < 2; ++ai)
; #pragma unroll
;             for (int m = 0; m < 4; ++m) {
;                 float o[8]; const float rv = rsqrtf(rowss[row0 + ai * HALF + m * 16] * (1.0f / 1024.0f) + 1e-6f);
; #pragma unroll
;                 for (int n = 0; n < 2; ++n)
; #pragma unroll
;                     for (int j = 0; j < 4; ++j) { const float g = acc[ai][0][m][n][j] * rv + bz[0][n][j], up = acc[ai][1][m][n][j] * rv + bz[1][n][j];
;                         o[4 * n + j] = g * __builtin_amdgcn_rcpf(1.0f + __expf(-g)) * up; }
;                 u32x4 w; w.x = pk_bf16(o[0], o[1]); w.y = pk_bf16(o[2], o[3]); w.z = pk_bf16(o[4], o[5]); w.w = pk_bf16(o[6], o[7]);
;                 *(u32x4*)(act + (size_t)(row0 + ai * HALF + m * 16) * 2816 + col0) = w;
;             }
	v_pk_fma_f32 v[66:67], v[66:67], v[80:81], v[176:177] op_sel_hi:[1,0,1]
	v_pk_mul_f32 v[76:77], v[76:77], v[82:83]
	s_nop 0
	v_pk_mul_f32 v[68:69], v[68:69], v[76:77]
	v_pk_fma_f32 v[76:77], v[78:79], v[80:81], v[248:249] op_sel_hi:[1,0,1]
	s_nop 0
	v_mul_f32_e32 v78, 0xbfb8aa3b, v76
	v_mul_f32_e32 v79, 0xbfb8aa3b, v77
	v_exp_f32_e32 v78, v78
	v_exp_f32_e32 v79, v79
	v_add_f32_e32 v78, 1.0, v78
	v_add_f32_e32 v79, 1.0, v79
	v_rcp_f32_e32 v78, v78
	v_rcp_f32_e32 v79, v79
	s_nop 0
	v_pk_mul_f32 v[76:77], v[76:77], v[78:79]
	s_nop 0
	v_pk_mul_f32 v[70:71], v[70:71], v[76:77]
	v_mul_f32_e32 v76, 0xbfb8aa3b, v72
	v_mul_f32_e32 v77, 0xbfb8aa3b, v73
	v_exp_f32_e32 v76, v76
	v_exp_f32_e32 v77, v77
	v_add_f32_e32 v76, 1.0, v76
	v_add_f32_e32 v77, 1.0, v77
	v_rcp_f32_e32 v76, v76
	v_rcp_f32_e32 v77, v77
	s_nop 0
	v_pk_mul_f32 v[72:73], v[72:73], v[76:77]
	s_nop 0
	v_pk_mul_f32 v[72:73], v[64:65], v[72:73]
	v_pk_fma_f32 v[64:65], v[74:75], v[80:81], v[244:245] op_sel_hi:[1,0,1]
	s_nop 0
	v_mul_f32_e32 v74, 0xbfb8aa3b, v64
	v_mul_f32_e32 v75, 0xbfb8aa3b, v65
	v_exp_f32_e32 v74, v74
	v_exp_f32_e32 v75, v75
	v_add_f32_e32 v74, 1.0, v74
	v_add_f32_e32 v75, 1.0, v75
	v_rcp_f32_e32 v74, v74
	v_rcp_f32_e32 v75, v75
	s_nop 0
	v_pk_mul_f32 v[64:65], v[64:65], v[74:75]
	s_nop 0
	v_pk_mul_f32 v[74:75], v[66:67], v[64:65]
	v_cvt_pk_bf16_f32 v64, v68, v69
	v_mad_i64_i32 v[68:69], s[4:5], v81, s12, v[134:135]
	v_cvt_pk_bf16_f32 v65, v70, v71
	v_cvt_pk_bf16_f32 v66, v72, v73
	v_cvt_pk_bf16_f32 v67, v74, v75
	v_lshl_add_u64 v[68:69], v[68:69], 0, v[136:137]
	global_store_dwordx4 v[68:69], v[64:67], off
	s_nop 0
	s_nop 0
	v_add_u32_e32 v65, 0x90, v156
	v_fmamk_f32 v64, v167, 0x3a800000, v227
	s_nop 0
	v_rsq_f32_e32 v64, v64
	s_nop 0
	v_pk_fma_f32 v[60:61], v[60:61], v[64:65], v[246:247] op_sel_hi:[1,0,1]
	v_pk_fma_f32 v[52:53], v[52:53], v[64:65], v[238:239] op_sel_hi:[1,0,1]
	v_mul_f32_e32 v66, 0xbfb8aa3b, v60
	v_mul_f32_e32 v67, 0xbfb8aa3b, v61
	v_exp_f32_e32 v66, v66
	v_exp_f32_e32 v67, v67
	v_pk_fma_f32 v[54:55], v[54:55], v[64:65], v[240:241] op_sel_hi:[1,0,1]
	v_pk_fma_f32 v[56:57], v[56:57], v[64:65], v[242:243] op_sel_hi:[1,0,1]
	v_add_f32_e32 v66, 1.0, v66
	v_add_f32_e32 v67, 1.0, v67
	v_rcp_f32_e32 v66, v66
	v_rcp_f32_e32 v67, v67
	v_pk_fma_f32 v[48:49], v[48:49], v[64:65], v[174:175] op_sel_hi:[1,0,1]
	v_pk_fma_f32 v[50:51], v[50:51], v[64:65], v[176:177] op_sel_hi:[1,0,1]
	v_pk_mul_f32 v[60:61], v[60:61], v[66:67]
	s_nop 0
	v_pk_mul_f32 v[52:53], v[52:53], v[60:61]
	v_pk_fma_f32 v[60:61], v[62:63], v[64:65], v[248:249] op_sel_hi:[1,0,1]
	s_nop 0
	v_mul_f32_e32 v62, 0xbfb8aa3b, v60
	v_mul_f32_e32 v63, 0xbfb8aa3b, v61
	v_exp_f32_e32 v62, v62
	v_exp_f32_e32 v63, v63
	v_add_f32_e32 v62, 1.0, v62
	v_add_f32_e32 v63, 1.0, v63
	v_rcp_f32_e32 v62, v62
	v_rcp_f32_e32 v63, v63
	s_nop 0
	v_pk_mul_f32 v[60:61], v[60:61], v[62:63]
	s_nop 0
	v_pk_mul_f32 v[54:55], v[54:55], v[60:61]
	v_mul_f32_e32 v60, 0xbfb8aa3b, v56
	v_mul_f32_e32 v61, 0xbfb8aa3b, v57
	v_exp_f32_e32 v60, v60
	v_exp_f32_e32 v61, v61
	v_add_f32_e32 v60, 1.0, v60
	v_add_f32_e32 v61, 1.0, v61
	v_rcp_f32_e32 v60, v60
	v_rcp_f32_e32 v61, v61
	s_nop 0
	v_pk_mul_f32 v[56:57], v[56:57], v[60:61]
	s_nop 0
	v_pk_mul_f32 v[56:57], v[48:49], v[56:57]
	v_pk_fma_f32 v[48:49], v[58:59], v[64:65], v[244:245] op_sel_hi:[1,0,1]
	s_nop 0
	v_mul_f32_e32 v58, 0xbfb8aa3b, v48
	v_mul_f32_e32 v59, 0xbfb8aa3b, v49
	v_exp_f32_e32 v58, v58
	v_exp_f32_e32 v59, v59
	v_add_f32_e32 v58, 1.0, v58
	v_add_f32_e32 v59, 1.0, v59
	v_rcp_f32_e32 v58, v58
	v_rcp_f32_e32 v59, v59
	s_nop 0
	v_pk_mul_f32 v[48:49], v[48:49], v[58:59]
	s_nop 0
	v_pk_mul_f32 v[58:59], v[50:51], v[48:49]
	v_cvt_pk_bf16_f32 v48, v52, v53
	v_mad_i64_i32 v[52:53], s[4:5], v65, s12, v[134:135]
	v_cvt_pk_bf16_f32 v49, v54, v55
	v_cvt_pk_bf16_f32 v50, v56, v57
	v_cvt_pk_bf16_f32 v51, v58, v59
	v_lshl_add_u64 v[52:53], v[52:53], 0, v[136:137]
	global_store_dwordx4 v[52:53], v[48:51], off
	s_nop 0
	s_nop 0
	v_add_u32_e32 v49, 0xa0, v156
	v_fmamk_f32 v48, v173, 0x3a800000, v227
	s_nop 0
	v_rsq_f32_e32 v48, v48
	s_nop 0
	v_pk_fma_f32 v[28:29], v[28:29], v[48:49], v[246:247] op_sel_hi:[1,0,1]
	v_pk_fma_f32 v[20:21], v[20:21], v[48:49], v[238:239] op_sel_hi:[1,0,1]
	v_mul_f32_e32 v50, 0xbfb8aa3b, v28
	v_mul_f32_e32 v51, 0xbfb8aa3b, v29
	v_exp_f32_e32 v50, v50
	v_exp_f32_e32 v51, v51
; __device__ __forceinline__ unsigned pk_bf16(float lo, float hi) { f32x2 v = {lo, hi}; bf16x2_t b = __builtin_convertvector(v, bf16x2_t); return __builtin_bit_cast(unsigned, b); }
; #define PG8_BAR __builtin_amdgcn_s_barrier()
;     __device__ __forceinline__ void operator()(const f32x4 (&acc)[2][2][4][2], const Unit& u, int wr, int wc, int fr, int fq) const {
;     ...
; #pragma unroll
;         for (int ai = 0; ai < 2; ++ai)
; #pragma unroll
;             for (int m = 0; m < 4; ++m) {
;                 float o[8]; const float rv = rsqrtf(rowss[row0 + ai * HALF + m * 16] * (1.0f / 1024.0f) + 1e-6f);
; #pragma unroll
;                 for (int n = 0; n < 2; ++n)
; #pragma unroll
;                     for (int j = 0; j < 4; ++j) { const float g = acc[ai][0][m][n][j] * rv + bz[0][n][j], up = acc[ai][1][m][n][j] * rv + bz[1][n][j];
;                         o[4 * n + j] = g * __builtin_amdgcn_rcpf(1.0f + __expf(-g)) * up; }
;                 u32x4 w; w.x = pk_bf16(o[0], o[1]); w.y = pk_bf16(o[2], o[3]); w.z = pk_bf16(o[4], o[5]); w.w = pk_bf16(o[6], o[7]);
;                 *(u32x4*)(act + (size_t)(row0 + ai * HALF + m * 16) * 2816 + col0) = w;
;             }
; template <class Epi, class Sched, bool ALIGN_EPI = false, bool SP2 = false, bool F16 = false>
; __device__ __forceinline__ void gemm_phase(PG8_LAS unsigned char* lds, const Gemm g, const Sched& S, const Epi& E) {
;     ...
;         if (!has_next) break;
; #pragma unroll
;         for (int a = 0; a < 2; ++a)
; #pragma unroll
;             for (int b = 0; b < 2; ++b)
; #pragma unroll
;                 for (int m = 0; m < 4; ++m)
; #pragma unroll
;                     for (int n = 0; n < 2; ++n) acc[a][b][m][n] = (f32x4){0.f, 0.f, 0.f, 0.f};
;         cur = nxt; cA = nA; cB = nB; ++ui;
;         if constexpr (ALIGN_EPI) { if (wr == 1) PG8_BAR; }
	v_pk_fma_f32 v[22:23], v[22:23], v[48:49], v[240:241] op_sel_hi:[1,0,1]
	v_pk_fma_f32 v[24:25], v[24:25], v[48:49], v[242:243] op_sel_hi:[1,0,1]
	v_add_f32_e32 v50, 1.0, v50
	v_add_f32_e32 v51, 1.0, v51
	v_rcp_f32_e32 v50, v50
	v_rcp_f32_e32 v51, v51
	v_pk_fma_f32 v[16:17], v[16:17], v[48:49], v[174:175] op_sel_hi:[1,0,1]
	v_pk_fma_f32 v[18:19], v[18:19], v[48:49], v[176:177] op_sel_hi:[1,0,1]
	v_pk_mul_f32 v[28:29], v[28:29], v[50:51]
	s_nop 0
	v_pk_mul_f32 v[20:21], v[20:21], v[28:29]
	v_pk_fma_f32 v[28:29], v[30:31], v[48:49], v[248:249] op_sel_hi:[1,0,1]
	s_nop 0
	v_mul_f32_e32 v30, 0xbfb8aa3b, v28
	v_mul_f32_e32 v31, 0xbfb8aa3b, v29
	v_exp_f32_e32 v30, v30
	v_exp_f32_e32 v31, v31
	v_add_f32_e32 v30, 1.0, v30
	v_add_f32_e32 v31, 1.0, v31
	v_rcp_f32_e32 v30, v30
	v_rcp_f32_e32 v31, v31
	s_nop 0
	v_pk_mul_f32 v[28:29], v[28:29], v[30:31]
	s_nop 0
	v_pk_mul_f32 v[22:23], v[22:23], v[28:29]
	v_mul_f32_e32 v28, 0xbfb8aa3b, v24
	v_mul_f32_e32 v29, 0xbfb8aa3b, v25
	v_exp_f32_e32 v28, v28
	v_exp_f32_e32 v29, v29
	v_add_f32_e32 v28, 1.0, v28
	v_add_f32_e32 v29, 1.0, v29
	v_rcp_f32_e32 v28, v28
	v_rcp_f32_e32 v29, v29
	s_nop 0
	v_pk_mul_f32 v[24:25], v[24:25], v[28:29]
	s_nop 0
	v_pk_mul_f32 v[24:25], v[16:17], v[24:25]
	v_pk_fma_f32 v[16:17], v[26:27], v[48:49], v[244:245] op_sel_hi:[1,0,1]
	s_nop 0
	v_mul_f32_e32 v26, 0xbfb8aa3b, v16
	v_mul_f32_e32 v27, 0xbfb8aa3b, v17
	v_exp_f32_e32 v26, v26
	v_exp_f32_e32 v27, v27
	v_add_f32_e32 v26, 1.0, v26
	v_add_f32_e32 v27, 1.0, v27
	v_rcp_f32_e32 v26, v26
	v_rcp_f32_e32 v27, v27
	s_nop 0
	v_pk_mul_f32 v[16:17], v[16:17], v[26:27]
	s_nop 0
	v_pk_mul_f32 v[26:27], v[18:19], v[16:17]
	v_cvt_pk_bf16_f32 v16, v20, v21
	v_mad_i64_i32 v[20:21], s[4:5], v49, s12, v[134:135]
	v_cvt_pk_bf16_f32 v17, v22, v23
	v_cvt_pk_bf16_f32 v18, v24, v25
	v_cvt_pk_bf16_f32 v19, v26, v27
	v_lshl_add_u64 v[20:21], v[20:21], 0, v[136:137]
	global_store_dwordx4 v[20:21], v[16:19], off
	s_nop 0
	s_nop 0
	v_add_u32_e32 v17, 0xb0, v156
	v_fmamk_f32 v16, v250, 0x3a800000, v227
	s_nop 0
	v_rsq_f32_e32 v16, v16
	s_nop 0
	v_pk_fma_f32 v[12:13], v[12:13], v[16:17], v[246:247] op_sel_hi:[1,0,1]
	v_pk_fma_f32 v[4:5], v[4:5], v[16:17], v[238:239] op_sel_hi:[1,0,1]
	v_mul_f32_e32 v18, 0xbfb8aa3b, v12
	v_mul_f32_e32 v19, 0xbfb8aa3b, v13
	v_exp_f32_e32 v18, v18
	v_exp_f32_e32 v19, v19
	v_pk_fma_f32 v[6:7], v[6:7], v[16:17], v[240:241] op_sel_hi:[1,0,1]
	v_pk_fma_f32 v[8:9], v[8:9], v[16:17], v[242:243] op_sel_hi:[1,0,1]
	v_add_f32_e32 v18, 1.0, v18
	v_add_f32_e32 v19, 1.0, v19
	v_rcp_f32_e32 v18, v18
	v_rcp_f32_e32 v19, v19
	v_pk_fma_f32 v[0:1], v[0:1], v[16:17], v[174:175] op_sel_hi:[1,0,1]
	v_pk_fma_f32 v[2:3], v[2:3], v[16:17], v[176:177] op_sel_hi:[1,0,1]
	s_andn2_b64 vcc, exec, s[40:41]
	v_pk_mul_f32 v[12:13], v[12:13], v[18:19]
	s_nop 0
	v_pk_mul_f32 v[4:5], v[4:5], v[12:13]
	v_pk_fma_f32 v[12:13], v[14:15], v[16:17], v[248:249] op_sel_hi:[1,0,1]
	s_nop 0
	v_mul_f32_e32 v14, 0xbfb8aa3b, v12
	v_mul_f32_e32 v15, 0xbfb8aa3b, v13
	v_exp_f32_e32 v14, v14
	v_exp_f32_e32 v15, v15
	v_add_f32_e32 v14, 1.0, v14
	v_add_f32_e32 v15, 1.0, v15
	v_rcp_f32_e32 v14, v14
	v_rcp_f32_e32 v15, v15
	s_nop 0
	v_pk_mul_f32 v[12:13], v[12:13], v[14:15]
	s_nop 0
	v_pk_mul_f32 v[6:7], v[6:7], v[12:13]
	v_mul_f32_e32 v12, 0xbfb8aa3b, v8
	v_mul_f32_e32 v13, 0xbfb8aa3b, v9
	v_exp_f32_e32 v12, v12
	v_exp_f32_e32 v13, v13
	v_add_f32_e32 v12, 1.0, v12
	v_add_f32_e32 v13, 1.0, v13
	v_rcp_f32_e32 v12, v12
	v_rcp_f32_e32 v13, v13
	s_nop 0
	v_pk_mul_f32 v[8:9], v[8:9], v[12:13]
	s_nop 0
	v_pk_mul_f32 v[8:9], v[0:1], v[8:9]
	v_pk_fma_f32 v[0:1], v[10:11], v[16:17], v[244:245] op_sel_hi:[1,0,1]
	s_nop 0
	v_mul_f32_e32 v10, 0xbfb8aa3b, v0
	v_mul_f32_e32 v11, 0xbfb8aa3b, v1
	v_exp_f32_e32 v10, v10
	v_exp_f32_e32 v11, v11
	v_add_f32_e32 v10, 1.0, v10
	v_add_f32_e32 v11, 1.0, v11
	v_rcp_f32_e32 v10, v10
	v_rcp_f32_e32 v11, v11
	s_nop 0
	v_pk_mul_f32 v[0:1], v[0:1], v[10:11]
	s_nop 0
	v_pk_mul_f32 v[10:11], v[2:3], v[0:1]
	v_cvt_pk_bf16_f32 v0, v4, v5
	v_mad_i64_i32 v[4:5], s[4:5], v17, s12, v[134:135]
	v_cvt_pk_bf16_f32 v1, v6, v7
	v_cvt_pk_bf16_f32 v2, v8, v9
	v_cvt_pk_bf16_f32 v3, v10, v11
	v_lshl_add_u64 v[4:5], v[4:5], 0, v[136:137]
	global_store_dwordx4 v[4:5], v[0:3], off
	s_cbranch_vccnz .LBB0_900
	s_andn2_b64 vcc, exec, s[0:1]
	s_cbranch_vccnz .LBB0_899
	s_barrier
	s_branch .LBB0_899
